# ret sample item: the 8 V-row loads issued together before the LDS barrier and waited once (were 8 dependent round trips)
# baseline (speedup 1.0000x reference)
; DI float bflo(unsigned u) { return __uint_as_float(u << 16); }
; DI float bfhi(unsigned u) { return __uint_as_float(u & 0xffff0000u); }
; DI void lds_barrier() { asm volatile("s_waitcnt lgkmcnt(0)" ::: "memory"); __builtin_amdgcn_s_barrier(); asm volatile("" ::: "memory"); }
; DI void ret_sample_item(const Params& p, int item, unsigned char* smem) {
;     ...
;     lds_barrier();
;     float* red = (float*)(smem + 40960);
;     float* vsh = (float*)(smem + 106496);
;     const int dv4 = tid & 127, dkq = tid >> 7;
;     f32x4 v[8], ao[8];
; #pragma unroll
;     for (int c = 0; c < 8; ++c) { const u32x2 vv = *(const u32x2*)(P1 + (size_t)(tok0 + c) * LDP1 + 2048 + h * 512 + 4 * dv4);
;         v[c] = (f32x4){bflo(vv.x), bfhi(vv.x), bflo(vv.y), bfhi(vv.y)}; ao[c] = (f32x4){0.f, 0.f, 0.f, 0.f};
;         if (dkq == 0) *(f32x4*)(vsh + c * 512 + 4 * dv4) = v[c]; }
;     const float sdec = expf(lg * 8.f);
;     const float* S0 = p.st_ret + (size_t)item * 131072 + 4 * dv4; float* So = p.out + O_RS + (size_t)item * 131072 + 4 * dv4;
; #pragma unroll 1
;     for (int dk0 = 64 * dkq; dk0 < 64 * dkq + 64; dk0 += 16) {
.LBB0_1351:
	s_or_b64 exec, exec, s[4:5]
	s_mul_i32 s1, s12, 0x3000
	s_mul_hi_i32 s0, s12, 0x3000
	s_add_u32 s1, s86, s1
	s_addc_u32 s4, s87, s0
	s_lshl_b32 s0, s3, 10
	s_add_u32 s0, s1, s0
	s_addc_u32 s1, s4, 0
	s_add_u32 s0, s0, 0x1000
	s_addc_u32 s1, s1, 0
	v_lshl_add_u64 v[4:5], s[0:1], 0, v[130:131]
	v_cmp_gt_u32_e64 s[4:5], s42, v132
	v_lshl_add_u32 v35, v2, 4, s43
	global_load_dwordx2 v[4:5], v[4:5], off
	s_lshl_b32 s3, s13, 1
	v_lshlrev_b32_e32 v130, 1, v149
	s_or_b32 s0, s12, 1
	s_mul_i32 s13, s0, 0x3000
	s_mul_hi_i32 s1, s0, 0x3000
	s_add_u32 s13, s86, s13
	s_addc_u32 s1, s87, s1
	s_add_u32 s26, s13, s3
	s_addc_u32 s27, s1, 0
	s_add_u32 s26, s26, 0x1000
	s_addc_u32 s27, s27, 0
	v_lshl_add_u64 v[6:7], s[26:27], 0, v[130:131]
	global_load_dwordx2 v[8:9], v[6:7], off
	s_or_b32 s14, s12, 2
	s_mul_i32 s13, s14, 0x3000
	s_mul_hi_i32 s1, s14, 0x3000
	s_add_u32 s13, s86, s13
	s_addc_u32 s1, s87, s1
	s_add_u32 s26, s13, s3
	s_addc_u32 s27, s1, 0
	s_add_u32 s26, s26, 0x1000
	s_addc_u32 s27, s27, 0
	v_lshl_add_u64 v[10:11], s[26:27], 0, v[130:131]
	global_load_dwordx2 v[12:13], v[10:11], off
	s_or_b32 s16, s12, 3
	s_mul_i32 s13, s16, 0x3000
	s_mul_hi_i32 s1, s16, 0x3000
	s_add_u32 s13, s86, s13
	s_addc_u32 s1, s87, s1
	s_add_u32 s26, s13, s3
	s_addc_u32 s27, s1, 0
	s_add_u32 s26, s26, 0x1000
	s_addc_u32 s27, s27, 0
	v_lshl_add_u64 v[14:15], s[26:27], 0, v[130:131]
	global_load_dwordx2 v[16:17], v[14:15], off
	s_or_b32 s18, s12, 4
	s_mul_i32 s13, s18, 0x3000
	s_mul_hi_i32 s1, s18, 0x3000
	s_add_u32 s13, s86, s13
	s_addc_u32 s1, s87, s1
	s_add_u32 s26, s13, s3
	s_addc_u32 s27, s1, 0
	s_add_u32 s26, s26, 0x1000
	s_addc_u32 s27, s27, 0
	v_lshl_add_u64 v[18:19], s[26:27], 0, v[130:131]
	global_load_dwordx2 v[20:21], v[18:19], off
	s_or_b32 s20, s12, 5
	s_mul_i32 s13, s20, 0x3000
	s_mul_hi_i32 s1, s20, 0x3000
	s_add_u32 s13, s86, s13
	s_addc_u32 s1, s87, s1
	s_add_u32 s26, s13, s3
	s_addc_u32 s27, s1, 0
	s_add_u32 s26, s26, 0x1000
	s_addc_u32 s27, s27, 0
	v_lshl_add_u64 v[22:23], s[26:27], 0, v[130:131]
	global_load_dwordx2 v[24:25], v[22:23], off
	s_or_b32 s22, s12, 6
	s_mul_i32 s13, s22, 0x3000
	s_mul_hi_i32 s1, s22, 0x3000
	s_add_u32 s13, s86, s13
	s_addc_u32 s1, s87, s1
	s_add_u32 s26, s13, s3
	s_addc_u32 s27, s1, 0
	s_add_u32 s26, s26, 0x1000
	s_addc_u32 s27, s27, 0
	v_lshl_add_u64 v[26:27], s[26:27], 0, v[130:131]
	global_load_dwordx2 v[28:29], v[26:27], off
	s_or_b32 s24, s12, 7
	s_mul_i32 s13, s24, 0x3000
	s_mul_hi_i32 s1, s24, 0x3000
	s_add_u32 s13, s86, s13
	s_addc_u32 s1, s87, s1
	s_add_u32 s26, s13, s3
	s_addc_u32 s27, s1, 0
	s_add_u32 s26, s26, 0x1000
	s_addc_u32 s27, s27, 0
	v_lshl_add_u64 v[30:31], s[26:27], 0, v[130:131]
	global_load_dwordx2 v[32:33], v[30:31], off
	s_waitcnt lgkmcnt(0)
	s_barrier
	s_waitcnt vmcnt(0)
	v_lshlrev_b32_e32 v2, 16, v4
	v_and_b32_e32 v3, 0xffff0000, v4
	v_lshlrev_b32_e32 v4, 16, v5
	v_and_b32_e32 v5, 0xffff0000, v5
	v_lshlrev_b32_e32 v6, 16, v8
	v_and_b32_e32 v7, 0xffff0000, v8
	v_lshlrev_b32_e32 v8, 16, v9
	v_and_b32_e32 v9, 0xffff0000, v9
	v_lshlrev_b32_e32 v10, 16, v12
	v_and_b32_e32 v11, 0xffff0000, v12
	v_lshlrev_b32_e32 v12, 16, v13
	v_and_b32_e32 v13, 0xffff0000, v13
	v_lshlrev_b32_e32 v14, 16, v16
	v_and_b32_e32 v15, 0xffff0000, v16
	v_lshlrev_b32_e32 v16, 16, v17
	v_and_b32_e32 v17, 0xffff0000, v17
	v_lshlrev_b32_e32 v18, 16, v20
	v_and_b32_e32 v19, 0xffff0000, v20
	v_lshlrev_b32_e32 v20, 16, v21
	v_and_b32_e32 v21, 0xffff0000, v21
	v_lshlrev_b32_e32 v22, 16, v24
	v_and_b32_e32 v23, 0xffff0000, v24
	v_lshlrev_b32_e32 v24, 16, v25
	v_and_b32_e32 v25, 0xffff0000, v25
	v_lshlrev_b32_e32 v26, 16, v28
	v_and_b32_e32 v27, 0xffff0000, v28
	v_lshlrev_b32_e32 v28, 16, v29
	v_and_b32_e32 v29, 0xffff0000, v29
	v_lshlrev_b32_e32 v30, 16, v32
	v_and_b32_e32 v31, 0xffff0000, v32
	v_lshlrev_b32_e32 v32, 16, v33
	v_and_b32_e32 v33, 0xffff0000, v33
	s_and_saveexec_b64 s[26:27], s[4:5]
	ds_write_b128 v35, v[2:5]
	ds_write_b128 v35, v[6:9] offset:2048
	ds_write_b128 v35, v[10:13] offset:4096
	ds_write_b128 v35, v[14:17] offset:6144
	ds_write_b128 v35, v[18:21] offset:8192
	ds_write_b128 v35, v[22:25] offset:10240
	ds_write_b128 v35, v[26:29] offset:12288
	ds_write_b128 v35, v[30:33] offset:14336
	s_or_b64 exec, exec, s[26:27]
	v_mul_f32_e32 v34, 0x41000000, v34
	v_mul_f32_e32 v35, 0x3fb8aa3b, v34
	v_fma_f32 v36, v34, s35, -v35
	v_rndne_f32_e32 v37, v35
	v_fmac_f32_e32 v36, 0x32a5705f, v34
	v_sub_f32_e32 v35, v35, v37
	v_add_f32_e32 v35, v35, v36
	v_exp_f32_e32 v35, v35
	v_cvt_i32_f32_e32 v36, v37
	v_cmp_ngt_f32_e32 vcc, s36, v34
	s_ashr_i32 s53, s52, 31
	s_lshl_b64 s[4:5], s[52:53], 19
	v_ldexp_f32 v35, v35, v36
	v_cndmask_b32_e32 v35, 0, v35, vcc
	v_cmp_nlt_f32_e32 vcc, s37, v34
	v_lshlrev_b32_e32 v34, 6, v148
	v_or_b32_e32 v150, 48, v34
	v_cndmask_b32_e32 v134, v146, v35, vcc
	v_and_b32_e32 v35, 0x7f, v132
	v_lshlrev_b32_e32 v130, 4, v35
	v_ashrrev_i32_e32 v35, 31, v34
	v_add_u32_e32 v151, -16, v34
	v_lshlrev_b64 v[34:35], 11, v[34:35]
	v_mov_b32_e32 v70, 0
	v_lshl_add_u64 v[34:35], s[4:5], 0, v[34:35]
	s_ashr_i32 s13, s12, 31
	s_ashr_i32 s1, s0, 31
	s_ashr_i32 s15, s14, 31
	s_ashr_i32 s17, s16, 31
	s_ashr_i32 s19, s18, 31
	s_ashr_i32 s21, s20, 31
	s_ashr_i32 s23, s22, 31
	s_ashr_i32 s25, s24, 31
	v_mov_b32_e32 v136, v134
	v_mov_b32_e32 v137, v134
	v_lshl_add_u32 v152, v148, 11, 0
	v_lshl_add_u64 v[138:139], s[68:69], 0, v[34:35]
	v_lshl_add_u64 v[140:141], s[76:77], 0, v[34:35]
	s_mov_b64 s[4:5], 0
	v_mov_b32_e32 v71, v70
	v_mov_b32_e32 v72, v70
	v_mov_b32_e32 v73, v70
	v_mov_b32_e32 v78, v70
	v_mov_b32_e32 v79, v70
	v_mov_b32_e32 v80, v70
	v_mov_b32_e32 v81, v70
	v_mov_b32_e32 v82, v70
	v_mov_b32_e32 v83, v70
	v_mov_b32_e32 v84, v70
	v_mov_b32_e32 v85, v70
	v_mov_b32_e32 v86, v70
	v_mov_b32_e32 v87, v70
	v_mov_b32_e32 v88, v70
	v_mov_b32_e32 v89, v70
	v_mov_b32_e32 v90, v70
	v_mov_b32_e32 v91, v70
	v_mov_b32_e32 v92, v70
	v_mov_b32_e32 v93, v70
	v_mov_b32_e32 v94, v70
	v_mov_b32_e32 v95, v70
	v_mov_b32_e32 v96, v70
	v_mov_b32_e32 v97, v70
	v_mov_b32_e32 v98, v70
	v_mov_b32_e32 v99, v70
	v_mov_b32_e32 v100, v70
	v_mov_b32_e32 v101, v70
	v_mov_b32_e32 v102, v70
	v_mov_b32_e32 v103, v70
	v_mov_b32_e32 v104, v70
	v_mov_b32_e32 v105, v70
